# loop-edge edit in the layer 1 pair loop: the stagger stub's wave-id readlane moved in front of the loop-top wait+barrier, hazard nop dropped
# baseline (speedup 1.0000x reference)
;     ...
;         for (int p = p0; p < npairs; ++p) {
;             asm volatile("s_waitcnt vmcnt(0)" ::: "memory");
;             __builtin_amdgcn_s_barrier(); asm volatile("" ::: "memory");
.LBB0_2104:
	v_readlane_b32 s98, v254, 11
	s_waitcnt vmcnt(0)
	s_barrier
	s_cmp_lt_u32 s98, 4
	s_cbranch_scc1 .Lstag_2104
	s_sleep 8
	s_setprio 1
